# GEMM unit prologue: accumulators zeroed with 64 v_mov_b64 of the inline 0 instead of 127 v_mov_b32 copies
# baseline (speedup 1.0000x reference)
;     ...
;         const bool has_next = S.next(ui + 1, nxt);
;         const char* nA = has_next ? (const char*)g.A + (size_t)nxt.pm * tstepA + (size_t)nxt.k0 * kstep : cA; const char* nB = has_next ? (const char*)g.Bt + (size_t)nxt.pn * tstep + (size_t)nxt.k0 * kstep : cB;
;     ...
; #pragma unroll
;         for (int a = 0; a < 2; ++a)
; #pragma unroll
;             for (int b = 0; b < 2; ++b)
; #pragma unroll
;                 for (int m = 0; m < 4; ++m)
; #pragma unroll
;                     for (int n = 0; n < 2; ++n) acc[a][b][m][n] = (f32x4){0.f, 0.f, 0.f, 0.f};
.LBB0_406:
	s_ashr_i32 s25, s24, 31
	s_lshl_b64 s[26:27], s[24:25], 20
	s_add_u32 s26, s80, s26
	s_addc_u32 s27, s81, s27
	s_and_b64 s[38:39], s[6:7], exec
	s_cselect_b32 s9, s27, s31
	s_cselect_b32 s25, s26, s30
	s_ashr_i32 s93, s92, 31
	s_lshl_b64 s[38:39], s[92:93], 20
	s_add_u32 s38, s22, s38
	s_addc_u32 s39, s23, s39
	s_and_b64 s[42:43], s[6:7], exec
	s_cselect_b32 s33, s39, s29
	s_cselect_b32 s40, s38, s28
	s_add_u32 s30, s30, 0x80080
	s_addc_u32 s31, s31, 0
	s_add_u32 s48, s28, 0x100
	v_mov_b32_e32 v2, 0
	s_addc_u32 s50, s29, 0
	s_mov_b32 s93, -2
	v_mov_b32_e32 v3, 0
	v_mov_b64_e32 v[4:5], 0
	v_mov_b64_e32 v[6:7], 0
	v_mov_b64_e32 v[8:9], 0
	v_mov_b64_e32 v[10:11], 0
	v_mov_b64_e32 v[12:13], 0
	v_mov_b64_e32 v[14:15], 0
	v_mov_b64_e32 v[16:17], 0
	v_mov_b64_e32 v[18:19], 0
	v_mov_b64_e32 v[20:21], 0
	v_mov_b64_e32 v[22:23], 0
	v_mov_b64_e32 v[24:25], 0
	v_mov_b64_e32 v[26:27], 0
	v_mov_b64_e32 v[28:29], 0
	v_mov_b64_e32 v[36:37], 0
	v_mov_b64_e32 v[38:39], 0
	v_mov_b64_e32 v[40:41], 0
	v_mov_b64_e32 v[42:43], 0
	v_mov_b64_e32 v[44:45], 0
	v_mov_b64_e32 v[46:47], 0
	v_mov_b64_e32 v[48:49], 0
	v_mov_b64_e32 v[50:51], 0
	v_mov_b64_e32 v[52:53], 0
	v_mov_b64_e32 v[54:55], 0
	v_mov_b64_e32 v[56:57], 0
	v_mov_b64_e32 v[58:59], 0
	v_mov_b64_e32 v[60:61], 0
	v_mov_b64_e32 v[62:63], 0
	v_mov_b64_e32 v[64:65], 0
	v_mov_b64_e32 v[66:67], 0
	v_mov_b64_e32 v[68:69], 0
	v_mov_b64_e32 v[70:71], 0
	v_mov_b64_e32 v[72:73], 0
	v_mov_b64_e32 v[74:75], 0
	v_mov_b64_e32 v[76:77], 0
	v_mov_b64_e32 v[78:79], 0
	v_mov_b64_e32 v[80:81], 0
	v_mov_b64_e32 v[82:83], 0
	v_mov_b64_e32 v[84:85], 0
	v_mov_b64_e32 v[86:87], 0
	v_mov_b64_e32 v[88:89], 0
	v_mov_b64_e32 v[90:91], 0
	v_mov_b64_e32 v[92:93], 0
	v_mov_b64_e32 v[94:95], 0
	v_mov_b64_e32 v[96:97], 0
	v_mov_b64_e32 v[98:99], 0
	v_mov_b64_e32 v[100:101], 0
	v_mov_b64_e32 v[102:103], 0
	v_mov_b64_e32 v[104:105], 0
	v_mov_b64_e32 v[106:107], 0
	v_mov_b64_e32 v[108:109], 0
	v_mov_b64_e32 v[110:111], 0
	v_mov_b64_e32 v[112:113], 0
	v_mov_b64_e32 v[114:115], 0
	v_mov_b64_e32 v[116:117], 0
	v_mov_b64_e32 v[118:119], 0
	v_mov_b64_e32 v[120:121], 0
	v_mov_b64_e32 v[122:123], 0
	v_mov_b64_e32 v[124:125], 0
	v_mov_b64_e32 v[126:127], 0
	v_mov_b64_e32 v[128:129], 0
	v_mov_b64_e32 v[130:131], 0
	v_mov_b64_e32 v[132:133], 0
	v_mov_b64_e32 v[134:135], 0

;     ...
; #pragma unroll
;         for (int a = 0; a < 2; ++a)
; #pragma unroll
;             for (int b = 0; b < 2; ++b)
; #pragma unroll
;                 for (int m = 0; m < 4; ++m)
; #pragma unroll
;                     for (int n = 0; n < 2; ++n) acc[a][b][m][n] = (f32x4){0.f, 0.f, 0.f, 0.f};
.LBB0_747:
	s_ashr_i32 s11, s10, 31
	s_lshl_b64 s[14:15], s[10:11], 18
	s_add_u32 s14, s22, s14
	s_addc_u32 s15, s23, s15
	s_and_b64 s[4:5], s[4:5], exec
	s_cselect_b32 s11, s15, s25
	s_cselect_b32 s33, s14, s24
	s_add_u32 s48, s24, 0x100
	v_mov_b32_e32 v2, 0
	s_addc_u32 s74, s25, 0
	s_mov_b32 s78, -2
	v_mov_b32_e32 v3, 0
	v_mov_b64_e32 v[4:5], 0
	v_mov_b64_e32 v[6:7], 0
	v_mov_b64_e32 v[8:9], 0
	v_mov_b64_e32 v[10:11], 0
	v_mov_b64_e32 v[12:13], 0
	v_mov_b64_e32 v[14:15], 0
	v_mov_b64_e32 v[16:17], 0
	v_mov_b64_e32 v[18:19], 0
	v_mov_b64_e32 v[20:21], 0
	v_mov_b64_e32 v[22:23], 0
	v_mov_b64_e32 v[24:25], 0
	v_mov_b64_e32 v[26:27], 0
	v_mov_b64_e32 v[28:29], 0
	v_mov_b64_e32 v[34:35], 0
	v_mov_b64_e32 v[36:37], 0
	v_mov_b64_e32 v[38:39], 0
	v_mov_b64_e32 v[40:41], 0
	v_mov_b64_e32 v[42:43], 0
	v_mov_b64_e32 v[44:45], 0
	v_mov_b64_e32 v[46:47], 0
	v_mov_b64_e32 v[48:49], 0
	v_mov_b64_e32 v[50:51], 0
	v_mov_b64_e32 v[52:53], 0
	v_mov_b64_e32 v[54:55], 0
	v_mov_b64_e32 v[56:57], 0
	v_mov_b64_e32 v[58:59], 0
	v_mov_b64_e32 v[60:61], 0
	v_mov_b64_e32 v[62:63], 0
	v_mov_b64_e32 v[64:65], 0
	v_mov_b64_e32 v[66:67], 0
	v_mov_b64_e32 v[68:69], 0
	v_mov_b64_e32 v[70:71], 0
	v_mov_b64_e32 v[72:73], 0
	v_mov_b64_e32 v[74:75], 0
	v_mov_b64_e32 v[76:77], 0
	v_mov_b64_e32 v[78:79], 0
	v_mov_b64_e32 v[80:81], 0
	v_mov_b64_e32 v[82:83], 0
	v_mov_b64_e32 v[84:85], 0
	v_mov_b64_e32 v[86:87], 0
	v_mov_b64_e32 v[88:89], 0
	v_mov_b64_e32 v[90:91], 0
	v_mov_b64_e32 v[92:93], 0
	v_mov_b64_e32 v[94:95], 0
	v_mov_b64_e32 v[96:97], 0
	v_mov_b64_e32 v[98:99], 0
	v_mov_b64_e32 v[100:101], 0
	v_mov_b64_e32 v[102:103], 0
	v_mov_b64_e32 v[104:105], 0
	v_mov_b64_e32 v[106:107], 0
	v_mov_b64_e32 v[108:109], 0
	v_mov_b64_e32 v[110:111], 0
	v_mov_b64_e32 v[112:113], 0
	v_mov_b64_e32 v[114:115], 0
	v_mov_b64_e32 v[116:117], 0
	v_mov_b64_e32 v[118:119], 0
	v_mov_b64_e32 v[120:121], 0
	v_mov_b64_e32 v[122:123], 0
	v_mov_b64_e32 v[124:125], 0
	v_mov_b64_e32 v[126:127], 0
	v_mov_b64_e32 v[128:129], 0
	v_mov_b64_e32 v[130:131], 0
	v_mov_b64_e32 v[132:133], 0

;     ...
; #pragma unroll
;         for (int a = 0; a < 2; ++a)
; #pragma unroll
;             for (int b = 0; b < 2; ++b)
; #pragma unroll
;                 for (int m = 0; m < 4; ++m)
; #pragma unroll
;                     for (int n = 0; n < 2; ++n) acc[a][b][m][n] = (f32x4){0.f, 0.f, 0.f, 0.f};
.LBB0_765:
	s_ashr_i32 s13, s12, 31
	s_lshl_b64 s[6:7], s[12:13], 17
	v_readlane_b32 s16, v255, 5
	v_readlane_b32 s17, v255, 6
	s_add_u32 s16, s16, s6
	s_addc_u32 s17, s17, s7
	s_and_b64 s[4:5], s[4:5], exec
	v_mov_b32_e32 v2, 0
	s_cselect_b32 s13, s17, s23
	s_cselect_b32 s33, s16, s22
	s_mov_b32 s28, 0
	s_mov_b64 s[4:5], -1
	s_mov_b64 s[26:27], 0
	v_mov_b32_e32 v3, 0
	v_mov_b64_e32 v[4:5], 0
	v_mov_b64_e32 v[6:7], 0
	v_mov_b64_e32 v[8:9], 0
	v_mov_b64_e32 v[10:11], 0
	v_mov_b64_e32 v[12:13], 0
	v_mov_b64_e32 v[14:15], 0
	v_mov_b64_e32 v[16:17], 0
	v_mov_b64_e32 v[18:19], 0
	v_mov_b64_e32 v[20:21], 0
	v_mov_b64_e32 v[22:23], 0
	v_mov_b64_e32 v[24:25], 0
	v_mov_b64_e32 v[26:27], 0
	v_mov_b64_e32 v[28:29], 0
	v_mov_b64_e32 v[34:35], 0
	v_mov_b64_e32 v[36:37], 0
	v_mov_b64_e32 v[38:39], 0
	v_mov_b64_e32 v[40:41], 0
	v_mov_b64_e32 v[42:43], 0
	v_mov_b64_e32 v[44:45], 0
	v_mov_b64_e32 v[46:47], 0
	v_mov_b64_e32 v[48:49], 0
	v_mov_b64_e32 v[50:51], 0
	v_mov_b64_e32 v[52:53], 0
	v_mov_b64_e32 v[54:55], 0
	v_mov_b64_e32 v[56:57], 0
	v_mov_b64_e32 v[58:59], 0
	v_mov_b64_e32 v[60:61], 0
	v_mov_b64_e32 v[62:63], 0
	v_mov_b64_e32 v[64:65], 0
	v_mov_b64_e32 v[66:67], 0
	v_mov_b64_e32 v[68:69], 0
	v_mov_b64_e32 v[70:71], 0
	v_mov_b64_e32 v[72:73], 0
	v_mov_b64_e32 v[74:75], 0
	v_mov_b64_e32 v[76:77], 0
	v_mov_b64_e32 v[78:79], 0
	v_mov_b64_e32 v[80:81], 0
	v_mov_b64_e32 v[82:83], 0
	v_mov_b64_e32 v[84:85], 0
	v_mov_b64_e32 v[86:87], 0
	v_mov_b64_e32 v[88:89], 0
	v_mov_b64_e32 v[90:91], 0
	v_mov_b64_e32 v[92:93], 0
	v_mov_b64_e32 v[94:95], 0
	v_mov_b64_e32 v[96:97], 0
	v_mov_b64_e32 v[98:99], 0
	v_mov_b64_e32 v[100:101], 0
	v_mov_b64_e32 v[102:103], 0
	v_mov_b64_e32 v[104:105], 0
	v_mov_b64_e32 v[106:107], 0
	v_mov_b64_e32 v[108:109], 0
	v_mov_b64_e32 v[110:111], 0
	v_mov_b64_e32 v[112:113], 0
	v_mov_b64_e32 v[114:115], 0
	v_mov_b64_e32 v[116:117], 0
	v_mov_b64_e32 v[118:119], 0
	v_mov_b64_e32 v[120:121], 0
	v_mov_b64_e32 v[122:123], 0
	v_mov_b64_e32 v[124:125], 0
	v_mov_b64_e32 v[126:127], 0
	v_mov_b64_e32 v[128:129], 0
	v_mov_b64_e32 v[130:131], 0
	v_mov_b64_e32 v[132:133], 0

;     ...
; #pragma unroll
;         for (int a = 0; a < 2; ++a)
; #pragma unroll
;             for (int b = 0; b < 2; ++b)
; #pragma unroll
;                 for (int m = 0; m < 4; ++m)
; #pragma unroll
;                     for (int n = 0; n < 2; ++n) acc[a][b][m][n] = (f32x4){0.f, 0.f, 0.f, 0.f};
.LBB0_1063:
	s_add_u32 s9, s30, 0x100
	v_mov_b32_e32 v2, 0
	s_addc_u32 s17, s31, 0
	s_mov_b32 s19, 2
	v_mov_b32_e32 v3, 0
	v_mov_b64_e32 v[4:5], 0
	v_mov_b64_e32 v[6:7], 0
	v_mov_b64_e32 v[8:9], 0
	v_mov_b64_e32 v[10:11], 0
	v_mov_b64_e32 v[12:13], 0
	v_mov_b64_e32 v[14:15], 0
	v_mov_b64_e32 v[16:17], 0
	v_mov_b64_e32 v[18:19], 0
	v_mov_b64_e32 v[20:21], 0
	v_mov_b64_e32 v[22:23], 0
	v_mov_b64_e32 v[24:25], 0
	v_mov_b64_e32 v[26:27], 0
	v_mov_b64_e32 v[28:29], 0
	v_mov_b64_e32 v[36:37], 0
	v_mov_b64_e32 v[38:39], 0
	v_mov_b64_e32 v[40:41], 0
	v_mov_b64_e32 v[42:43], 0
	v_mov_b64_e32 v[44:45], 0
	v_mov_b64_e32 v[46:47], 0
	v_mov_b64_e32 v[48:49], 0
	v_mov_b64_e32 v[50:51], 0
	v_mov_b64_e32 v[52:53], 0
	v_mov_b64_e32 v[54:55], 0
	v_mov_b64_e32 v[56:57], 0
	v_mov_b64_e32 v[58:59], 0
	v_mov_b64_e32 v[60:61], 0
	v_mov_b64_e32 v[62:63], 0
	v_mov_b64_e32 v[64:65], 0
	v_mov_b64_e32 v[66:67], 0
	v_mov_b64_e32 v[68:69], 0
	v_mov_b64_e32 v[70:71], 0
	v_mov_b64_e32 v[84:85], 0
	v_mov_b64_e32 v[86:87], 0
	v_mov_b64_e32 v[92:93], 0
	v_mov_b64_e32 v[94:95], 0
	v_mov_b64_e32 v[96:97], 0
	v_mov_b64_e32 v[98:99], 0
	v_mov_b64_e32 v[100:101], 0
	v_mov_b64_e32 v[102:103], 0
	v_mov_b64_e32 v[104:105], 0
	v_mov_b64_e32 v[106:107], 0
	v_mov_b64_e32 v[108:109], 0
	v_mov_b64_e32 v[110:111], 0
	v_mov_b64_e32 v[112:113], 0
	v_mov_b64_e32 v[114:115], 0
	v_mov_b64_e32 v[116:117], 0
	v_mov_b64_e32 v[118:119], 0
	v_mov_b64_e32 v[120:121], 0
	v_mov_b64_e32 v[122:123], 0
	v_mov_b64_e32 v[124:125], 0
	v_mov_b64_e32 v[126:127], 0
	v_mov_b64_e32 v[128:129], 0
	v_mov_b64_e32 v[130:131], 0
	v_mov_b64_e32 v[132:133], 0
	v_mov_b64_e32 v[134:135], 0
	v_mov_b64_e32 v[136:137], 0
	v_mov_b64_e32 v[138:139], 0
	v_mov_b64_e32 v[140:141], 0
	v_mov_b64_e32 v[142:143], 0
	v_mov_b64_e32 v[144:145], 0
	v_mov_b64_e32 v[146:147], 0
	v_mov_b64_e32 v[148:149], 0
	v_mov_b64_e32 v[150:151], 0

;     ...
;         const bool has_next = S.next(ui + 1, nxt);
;         const char* nA = has_next ? (const char*)g.A + (size_t)nxt.pm * tstepA + (size_t)nxt.k0 * kstep : cA; const char* nB = has_next ? (const char*)g.Bt + (size_t)nxt.pn * tstep + (size_t)nxt.k0 * kstep : cB;
;         for (int t = 0; t < nt; t += 2) {
;             const bool last = (t == nt - 2);
;             const char* a1 = cA + (size_t)(t + 1) * kstep;
;             const char* a2 = last ? nA : cA + (size_t)(t + 2) * kstep; const char* b2 = last ? nB : cB + (size_t)(t + 2) * kstep;
;             const char* a3 = a2 + kstep; const char* b3 = b2 + kstep;
;     ...
; #pragma unroll
;         for (int a = 0; a < 2; ++a)
; #pragma unroll
;             for (int b = 0; b < 2; ++b)
; #pragma unroll
;                 for (int m = 0; m < 4; ++m)
; #pragma unroll
;                     for (int n = 0; n < 2; ++n) acc[a][b][m][n] = (f32x4){0.f, 0.f, 0.f, 0.f};
;         cur = nxt; cA = nA; cB = nB; nt = cur.nt; ++ui;
.LBB0_1331:
	s_ashr_i32 s11, s10, 31
	s_lshl_b64 s[12:13], s[10:11], 20
	s_add_u32 s12, s80, s12
	s_addc_u32 s13, s81, s13
	s_and_b64 s[14:15], s[16:17], exec
	s_cselect_b32 s11, s13, s25
	s_cselect_b32 s48, s12, s24
	s_ashr_i32 s9, s8, 31
	s_lshl_b64 s[14:15], s[8:9], 20
	v_readlane_b32 s28, v254, 55
	v_readlane_b32 s29, v254, 56
	s_add_u32 s14, s28, s14
	s_addc_u32 s15, s29, s15
	s_and_b64 s[28:29], s[16:17], exec
	s_cselect_b32 s9, s15, s27
	s_cselect_b32 s33, s14, s26
	s_add_u32 s24, s24, 0x80080
	s_addc_u32 s25, s25, 0
	s_add_u32 s74, s26, 0x100
	v_mov_b32_e32 v2, 0
	s_addc_u32 s78, s27, 0
	s_mov_b32 s79, -2
	v_mov_b32_e32 v3, 0
	v_mov_b64_e32 v[4:5], 0
	v_mov_b64_e32 v[6:7], 0
	v_mov_b64_e32 v[8:9], 0
	v_mov_b64_e32 v[10:11], 0
	v_mov_b64_e32 v[12:13], 0
	v_mov_b64_e32 v[14:15], 0
	v_mov_b64_e32 v[16:17], 0
	v_mov_b64_e32 v[18:19], 0
	v_mov_b64_e32 v[20:21], 0
	v_mov_b64_e32 v[22:23], 0
	v_mov_b64_e32 v[24:25], 0
	v_mov_b64_e32 v[26:27], 0
	v_mov_b64_e32 v[28:29], 0
	v_mov_b64_e32 v[34:35], 0
	v_mov_b64_e32 v[36:37], 0
	v_mov_b64_e32 v[38:39], 0
	v_mov_b64_e32 v[40:41], 0
	v_mov_b64_e32 v[42:43], 0
	v_mov_b64_e32 v[44:45], 0
	v_mov_b64_e32 v[46:47], 0
	v_mov_b64_e32 v[48:49], 0
	v_mov_b64_e32 v[50:51], 0
	v_mov_b64_e32 v[52:53], 0
	v_mov_b64_e32 v[54:55], 0
	v_mov_b64_e32 v[56:57], 0
	v_mov_b64_e32 v[58:59], 0
	v_mov_b64_e32 v[60:61], 0
	v_mov_b64_e32 v[62:63], 0
	v_mov_b64_e32 v[64:65], 0
	v_mov_b64_e32 v[66:67], 0
	v_mov_b64_e32 v[68:69], 0
	v_mov_b64_e32 v[70:71], 0
	v_mov_b64_e32 v[72:73], 0
	v_mov_b64_e32 v[74:75], 0
	v_mov_b64_e32 v[76:77], 0
	v_mov_b64_e32 v[78:79], 0
	v_mov_b64_e32 v[80:81], 0
	v_mov_b64_e32 v[82:83], 0
	v_mov_b64_e32 v[84:85], 0
	v_mov_b64_e32 v[86:87], 0
	v_mov_b64_e32 v[88:89], 0
	v_mov_b64_e32 v[90:91], 0
	v_mov_b64_e32 v[92:93], 0
	v_mov_b64_e32 v[110:111], 0
	v_mov_b64_e32 v[112:113], 0
	v_mov_b64_e32 v[114:115], 0
	v_mov_b64_e32 v[116:117], 0
	v_mov_b64_e32 v[118:119], 0
	v_mov_b64_e32 v[120:121], 0
	v_mov_b64_e32 v[122:123], 0
	v_mov_b64_e32 v[124:125], 0
	v_mov_b64_e32 v[126:127], 0
	v_mov_b64_e32 v[128:129], 0
	v_mov_b64_e32 v[130:131], 0
	v_mov_b64_e32 v[132:133], 0
	v_mov_b64_e32 v[134:135], 0
	v_mov_b64_e32 v[136:137], 0
	v_mov_b64_e32 v[138:139], 0
	v_mov_b64_e32 v[140:141], 0
	v_mov_b64_e32 v[142:143], 0
	v_mov_b64_e32 v[144:145], 0
	v_mov_b64_e32 v[146:147], 0
	v_mov_b64_e32 v[148:149], 0

;     ...
;         const bool has_next = S.next(ui + 1, nxt);
;         const char* nA = has_next ? (const char*)g.A + (size_t)nxt.pm * tstepA + (size_t)nxt.k0 * kstep : cA; const char* nB = has_next ? (const char*)g.Bt + (size_t)nxt.pn * tstep + (size_t)nxt.k0 * kstep : cB;
;         for (int t = 0; t < nt; t += 2) {
;             const bool last = (t == nt - 2);
;             const char* a1 = cA + (size_t)(t + 1) * kstep;
;             const char* a2 = last ? nA : cA + (size_t)(t + 2) * kstep; const char* b2 = last ? nB : cB + (size_t)(t + 2) * kstep;
;             const char* a3 = a2 + kstep; const char* b3 = b2 + kstep;
;     ...
; #pragma unroll
;         for (int a = 0; a < 2; ++a)
; #pragma unroll
;             for (int b = 0; b < 2; ++b)
; #pragma unroll
;                 for (int m = 0; m < 4; ++m)
; #pragma unroll
;                     for (int n = 0; n < 2; ++n) acc[a][b][m][n] = (f32x4){0.f, 0.f, 0.f, 0.f};
;         cur = nxt; cA = nA; cB = nB; nt = cur.nt; ++ui;
.LBB0_1453:
	s_add_u32 s9, s30, 0x100
	v_mov_b32_e32 v2, 0
	s_addc_u32 s23, s31, 0
	s_mov_b32 s25, 2
	v_mov_b32_e32 v3, 0
	v_mov_b64_e32 v[4:5], 0
	v_mov_b64_e32 v[6:7], 0
	v_mov_b64_e32 v[8:9], 0
	v_mov_b64_e32 v[10:11], 0
	v_mov_b64_e32 v[12:13], 0
	v_mov_b64_e32 v[14:15], 0
	v_mov_b64_e32 v[16:17], 0
	v_mov_b64_e32 v[18:19], 0
	v_mov_b64_e32 v[20:21], 0
	v_mov_b64_e32 v[22:23], 0
	v_mov_b64_e32 v[24:25], 0
	v_mov_b64_e32 v[26:27], 0
	v_mov_b64_e32 v[28:29], 0
	v_mov_b64_e32 v[36:37], 0
	v_mov_b64_e32 v[38:39], 0
	v_mov_b64_e32 v[40:41], 0
	v_mov_b64_e32 v[42:43], 0
	v_mov_b64_e32 v[44:45], 0
	v_mov_b64_e32 v[46:47], 0
	v_mov_b64_e32 v[48:49], 0
	v_mov_b64_e32 v[50:51], 0
	v_mov_b64_e32 v[52:53], 0
	v_mov_b64_e32 v[54:55], 0
	v_mov_b64_e32 v[56:57], 0
	v_mov_b64_e32 v[58:59], 0
	v_mov_b64_e32 v[60:61], 0
	v_mov_b64_e32 v[62:63], 0
	v_mov_b64_e32 v[64:65], 0
	v_mov_b64_e32 v[66:67], 0
	v_mov_b64_e32 v[68:69], 0
	v_mov_b64_e32 v[70:71], 0
	v_mov_b64_e32 v[84:85], 0
	v_mov_b64_e32 v[86:87], 0
	v_mov_b64_e32 v[92:93], 0
	v_mov_b64_e32 v[94:95], 0
	v_mov_b64_e32 v[96:97], 0
	v_mov_b64_e32 v[98:99], 0
	v_mov_b64_e32 v[100:101], 0
	v_mov_b64_e32 v[102:103], 0
	v_mov_b64_e32 v[104:105], 0
	v_mov_b64_e32 v[106:107], 0
	v_mov_b64_e32 v[108:109], 0
	v_mov_b64_e32 v[110:111], 0
	v_mov_b64_e32 v[112:113], 0
	v_mov_b64_e32 v[114:115], 0
	v_mov_b64_e32 v[116:117], 0
	v_mov_b64_e32 v[118:119], 0
	v_mov_b64_e32 v[120:121], 0
	v_mov_b64_e32 v[122:123], 0
	v_mov_b64_e32 v[124:125], 0
	v_mov_b64_e32 v[126:127], 0
	v_mov_b64_e32 v[128:129], 0
	v_mov_b64_e32 v[130:131], 0
	v_mov_b64_e32 v[132:133], 0
	v_mov_b64_e32 v[134:135], 0
	v_mov_b64_e32 v[136:137], 0
	v_mov_b64_e32 v[138:139], 0
	v_mov_b64_e32 v[140:141], 0
	v_mov_b64_e32 v[142:143], 0
	v_mov_b64_e32 v[144:145], 0
	v_mov_b64_e32 v[146:147], 0
	v_mov_b64_e32 v[148:149], 0
	v_mov_b64_e32 v[150:151], 0
